# v50 plus barrier before FF2: when every workgroup sits on the XCC bid&7 (checked at kernel start), the XCC's last arriver releases its own XCC directly (no write-back, no chip-wide arrival); full barr
# speedup vs baseline: 1.0185x; 1.0028x over previous
.LBB0_6:
	s_or_b64 exec, exec, s[4:5]
	s_waitcnt lgkmcnt(0)
	s_barrier
	s_add_u32 s96, s54, 0x4000
	s_getreg_b32 s0, hwreg(HW_REG_XCC_ID, 0, 4)
	s_addc_u32 s97, s55, 0
	s_and_b32 s90, s0, 15
	v_cmp_eq_u32_e64 s[14:15], 0, v0
	s_and_saveexec_b64 s[4:5], s[14:15]
	s_cbranch_execz .LBB0_9
	s_and_b32 s98, s38, 7
	s_cmp_eq_u32 s98, s90
	s_cbranch_scc1 .Lplace_ok
	v_mov_b32_e32 v232, 0x18000
	v_mov_b32_e32 v233, 1
	global_atomic_add v232, v233, s[54:55]
.Lplace_ok:
	s_mov_b64 s[6:7], exec
	v_mbcnt_lo_u32_b32 v2, s6, 0
	v_mbcnt_hi_u32_b32 v2, s7, v2
	v_cmp_eq_u32_e32 vcc, 0, v2
	s_and_b64 s[0:1], exec, vcc
	s_mov_b64 exec, s[0:1]
	s_cbranch_execz .LBB0_9
	s_lshl_b32 s0, s90, 8
	s_bcnt1_i32_b64 s1, s[6:7]
	v_mov_b32_e32 v2, s0
	v_mov_b32_e32 v3, s1
	global_atomic_add v2, v3, s[96:97] offset:1024

.LBB0_604:
	s_getreg_b32 s98, hwreg(HW_REG_XCC_ID, 0, 4)
	s_lshl_b32 s98, s98, 8
	v_mov_b32_e32 v1, 0x21160
	ds_read_b64 v[2:3], v1
	v_mov_b32_e32 v4, s98
	v_add_u32_e32 v4, 0x5400, v4
	v_mov_b32_e32 v5, 1
	global_atomic_add v6, v4, v5, s[54:55] sc0
	v_mov_b32_e32 v8, 0x18000
	global_load_dword v8, v8, s[54:55] sc1
	buffer_inv sc1
	v_add_u32_e32 v7, 0x1000, v4
	s_waitcnt lgkmcnt(0)
	v_mul_u32_u24_e32 v2, 6, v2
	v_mul_u32_u24_e32 v3, 6, v3
	s_waitcnt vmcnt(1)
	v_add_u32_e32 v6, 1, v6
	v_cmp_ne_u32_e32 vcc, v6, v2
	s_cbranch_vccnz .Lgb4_6_follow
	v_cmp_ne_u32_e32 vcc, 0, v8
	s_cbranch_vccnz .Lgb4_6_full
	global_atomic_add v7, v5, s[54:55]
	s_branch .Lgb4_6_acq
.Lgb4_6_full:
	buffer_wbl2 sc1
	s_waitcnt vmcnt(0)
	v_mov_b32_e32 v4, 0x7400
	global_atomic_add v6, v4, v5, s[54:55] sc0
	s_waitcnt vmcnt(0)
	v_add_u32_e32 v6, 1, v6
	v_cmp_ne_u32_e32 vcc, v6, v3
	s_cbranch_vccnz .Lgb4_6_follow
	v_mov_b32_e32 v4, 0x6400
	global_atomic_add v4, v5, s[54:55]
	global_atomic_add v4, v5, s[54:55] offset:256
	global_atomic_add v4, v5, s[54:55] offset:512
	global_atomic_add v4, v5, s[54:55] offset:768
	global_atomic_add v4, v5, s[54:55] offset:1024
	global_atomic_add v4, v5, s[54:55] offset:1280
	global_atomic_add v4, v5, s[54:55] offset:1536
	global_atomic_add v4, v5, s[54:55] offset:1792
	global_atomic_add v4, v5, s[54:55] offset:2048
	global_atomic_add v4, v5, s[54:55] offset:2304
	global_atomic_add v4, v5, s[54:55] offset:2560
	global_atomic_add v4, v5, s[54:55] offset:2816
	global_atomic_add v4, v5, s[54:55] offset:3072
	global_atomic_add v4, v5, s[54:55] offset:3328
	global_atomic_add v4, v5, s[54:55] offset:3584
	global_atomic_add v4, v5, s[54:55] offset:3840
	s_branch .Lgb4_6_acq
